# attention: q_norm/k_norm weight vectors prefetched at unit top with q/k/v loads (was 10 serialised load+vmcnt(0) groups); on top of spool fix
# speedup vs baseline: 1.0095x; 1.0049x over previous
.LBB0_262:
	v_readfirstlane_b32 s0, v0
	s_mov_b32 s22, s72
	s_ashr_i32 s72, s12, 5
	s_lshr_b32 s15, s0, 7
	s_lshr_b32 s0, s0, 5
	s_bfe_u32 s16, s12, 0x40001
	s_ashr_i32 s73, s72, 31
	s_and_b32 s14, s0, 2
	s_lshl_b64 s[74:75], s[72:73], 11
	s_lshl_b32 s73, s16, 7
	s_or_b32 s13, s14, 1
	v_or_b32_e32 v18, s73, v1
	s_lshl_b32 s17, s14, 5
	s_lshl_b32 s18, s13, 5
	s_and_b32 s19, s12, 1
	v_or_b32_e32 v2, s17, v18
	v_or_b32_e32 v18, s18, v18
	s_lshl_b32 s4, s19, 2
	v_or_b32_e32 v192, s74, v2
	v_or_b32_e32 v190, s74, v18
	s_add_i32 s15, s15, s4
	v_mad_u64_u32 v[2:3], s[4:5], v192, s7, v[184:185]
	v_mad_u64_u32 v[18:19], s[4:5], v190, s7, v[184:185]
	v_mad_i32_i24 v3, s75, v201, v3
	s_lshl_b32 s0, s15, 7
	v_mad_i32_i24 v19, s75, v201, v19
	v_lshl_add_u64 v[2:3], v[2:3], 0, s[0:1]
	v_lshl_add_u64 v[18:19], v[18:19], 0, s[0:1]
	v_lshl_add_u64 v[2:3], v[2:3], 0, v[186:187]
	v_lshl_add_u64 v[18:19], v[18:19], 0, v[186:187]
	global_load_dwordx4 v[14:17], v[2:3], off offset:1024
	global_load_dwordx4 v[10:13], v[2:3], off offset:1056
	global_load_dwordx4 v[6:9], v[2:3], off offset:1088
	s_nop 0
	global_load_dwordx4 v[2:5], v[2:3], off offset:1120
	s_nop 0
	global_load_dwordx4 v[30:33], v[18:19], off offset:1024
	global_load_dwordx4 v[26:29], v[18:19], off offset:1056
	global_load_dwordx4 v[22:25], v[18:19], off offset:1088
	s_nop 0
	global_load_dwordx4 v[18:21], v[18:19], off offset:1120
	global_load_dwordx4 v[118:121], v[182:183], off
	global_load_dwordx4 v[122:125], v[182:183], off offset:16
	global_load_dwordx4 v[126:129], v[182:183], off offset:32
	global_load_dwordx4 v[130:133], v[182:183], off offset:48
	global_load_dwordx4 v[134:137], v[182:183], off offset:64
	global_load_dwordx4 v[138:141], v[182:183], off offset:80
	global_load_dwordx4 v[142:145], v[182:183], off offset:96
	global_load_dwordx4 v[252:255], v[182:183], off offset:112
	global_load_dwordx4 v[216:219], v[180:181], off
	global_load_dwordx4 v[220:223], v[180:181], off offset:16
	global_load_dwordx4 v[224:227], v[180:181], off offset:64
	global_load_dwordx4 v[228:231], v[180:181], off offset:80
	global_load_dwordx4 v[232:235], v[180:181], off offset:128
	global_load_dwordx4 v[236:239], v[180:181], off offset:144
	global_load_dwordx4 v[240:243], v[180:181], off offset:192
	global_load_dwordx4 v[248:251], v[180:181], off offset:208
	s_addk_i32 s73, 0xff80
	v_add_u32_e32 v170, s73, v173
	v_lshl_add_u64 v[34:35], s[74:75], 0, v[170:171]
	v_mad_u64_u32 v[36:37], s[4:5], v34, s7, v[184:185]
	v_mad_i32_i24 v37, v35, s7, v37
	s_lshl_b32 s0, s19, 7
	v_mov_b32_e32 v193, s75
	v_cmp_lt_i32_e32 vcc, -1, v170
	v_lshl_add_u64 v[50:51], v[36:37], 0, s[0:1]
	v_mov_b32_e32 v46, 0
	v_mov_b32_e32 v47, 0
	v_mov_b32_e32 v48, 0
	v_mov_b32_e32 v49, 0
	s_and_saveexec_b64 s[4:5], vcc
	s_cbranch_execz .LBB0_264
	v_lshlrev_b32_e32 v170, 1, v172
	v_lshl_add_u64 v[34:35], v[50:51], 0, v[170:171]
	global_load_dwordx4 v[46:49], v[34:35], off offset:2304

.LBB0_272:
	s_or_b64 exec, exec, s[4:5]
	v_pk_mul_f32 v[50:51], v[62:63], v[62:63]
	v_pk_mul_f32 v[52:53], v[64:65], v[64:65]
	v_add_f32_e32 v50, v51, v50
	v_add_f32_e32 v50, v52, v50
	v_pk_mul_f32 v[54:55], v[66:67], v[66:67]
	v_add_f32_e32 v50, v53, v50
	v_add_f32_e32 v50, v54, v50
	v_pk_mul_f32 v[56:57], v[68:69], v[68:69]
	v_add_f32_e32 v50, v55, v50
	v_add_f32_e32 v50, v56, v50
	v_pk_mul_f32 v[58:59], v[70:71], v[70:71]
	v_add_f32_e32 v50, v57, v50
	v_add_f32_e32 v50, v58, v50
	v_pk_mul_f32 v[60:61], v[72:73], v[72:73]
	v_add_f32_e32 v50, v59, v50
	v_add_f32_e32 v50, v60, v50
	v_pk_mul_f32 v[94:95], v[74:75], v[74:75]
	v_add_f32_e32 v50, v61, v50
	v_add_f32_e32 v50, v94, v50
	v_pk_mul_f32 v[96:97], v[76:77], v[76:77]
	v_add_f32_e32 v50, v95, v50
	v_add_f32_e32 v50, v96, v50
	v_pk_mul_f32 v[98:99], v[78:79], v[78:79]
	v_add_f32_e32 v50, v97, v50
	v_add_f32_e32 v50, v98, v50
	v_pk_mul_f32 v[100:101], v[80:81], v[80:81]
	v_add_f32_e32 v50, v99, v50
	v_add_f32_e32 v50, v100, v50
	v_pk_mul_f32 v[102:103], v[92:93], v[92:93]
	v_add_f32_e32 v50, v101, v50
	v_add_f32_e32 v50, v102, v50
	v_pk_mul_f32 v[104:105], v[82:83], v[82:83]
	v_add_f32_e32 v50, v103, v50
	v_add_f32_e32 v50, v104, v50
	v_pk_mul_f32 v[106:107], v[84:85], v[84:85]
	v_add_f32_e32 v50, v105, v50
	v_add_f32_e32 v50, v106, v50
	v_pk_mul_f32 v[108:109], v[86:87], v[86:87]
	v_add_f32_e32 v50, v107, v50
	v_add_f32_e32 v50, v108, v50
	v_pk_mul_f32 v[110:111], v[88:89], v[88:89]
	v_add_f32_e32 v50, v109, v50
	v_add_f32_e32 v50, v110, v50
	v_pk_mul_f32 v[112:113], v[90:91], v[90:91]
	v_add_f32_e32 v50, v111, v50
	v_add_f32_e32 v50, v112, v50
	v_add_f32_e32 v50, v113, v50
	ds_bpermute_b32 v51, v198, v50
	s_cmp_eq_u32 s16, 15
	v_readlane_b32 s20, v247, 34
	s_cselect_b64 s[4:5], -1, 0
	v_readlane_b32 s21, v247, 35
	s_waitcnt lgkmcnt(0)
	v_add_f32_e32 v50, v50, v51
	v_fmamk_f32 v50, v50, 0x3c800000, v202
	v_rsq_f32_e32 v94, v50
	s_waitcnt vmcnt(0)
	v_mov_b64_e32 v[50:51], v[130:131]
	v_mov_b64_e32 v[52:53], v[132:133]
	v_mov_b64_e32 v[54:55], v[126:127]
	v_mov_b64_e32 v[56:57], v[128:129]
	v_mov_b64_e32 v[58:59], v[122:123]
	v_mov_b64_e32 v[60:61], v[124:125]
	v_mov_b64_e32 v[96:97], v[118:119]
	v_mov_b64_e32 v[98:99], v[120:121]
	s_and_b64 s[20:21], s[4:5], s[20:21]
	s_lshl_b32 s74, s72, 7
	v_pk_mul_f32 v[66:67], v[66:67], v[94:95] op_sel_hi:[1,0]
	v_pk_mul_f32 v[62:63], v[62:63], v[94:95] op_sel_hi:[1,0]
	v_pk_mul_f32 v[64:65], v[64:65], v[94:95] op_sel_hi:[1,0]
	v_pk_mul_f32 v[82:83], v[82:83], v[94:95] op_sel_hi:[1,0]
	v_pk_mul_f32 v[78:79], v[78:79], v[94:95] op_sel_hi:[1,0]
	v_pk_mul_f32 v[80:81], v[80:81], v[94:95] op_sel_hi:[1,0]
	v_pk_mul_f32 v[92:93], v[92:93], v[94:95] op_sel_hi:[1,0]
	s_waitcnt vmcnt(0)
	v_pk_mul_f32 v[58:59], v[58:59], v[66:67]
	v_pk_mul_f32 v[66:67], v[68:69], v[94:95] op_sel_hi:[1,0]
	v_pk_mul_f32 v[62:63], v[96:97], v[62:63]
	v_pk_mul_f32 v[60:61], v[60:61], v[66:67]
	v_pk_mul_f32 v[66:67], v[70:71], v[94:95] op_sel_hi:[1,0]
	v_pk_mul_f32 v[64:65], v[98:99], v[64:65]
	v_pk_mul_f32 v[54:55], v[54:55], v[66:67]
	v_pk_mul_f32 v[66:67], v[72:73], v[94:95] op_sel_hi:[1,0]
	s_nop 0
	v_pk_mul_f32 v[56:57], v[56:57], v[66:67]
	v_pk_mul_f32 v[66:67], v[74:75], v[94:95] op_sel_hi:[1,0]
	s_nop 0
	v_pk_mul_f32 v[50:51], v[50:51], v[66:67]
	v_pk_mul_f32 v[66:67], v[76:77], v[94:95] op_sel_hi:[1,0]
	s_nop 0
	v_pk_mul_f32 v[52:53], v[52:53], v[66:67]
	v_mov_b64_e32 v[66:67], v[252:253]
	v_mov_b64_e32 v[68:69], v[254:255]
	v_mov_b64_e32 v[70:71], v[142:143]
	v_mov_b64_e32 v[72:73], v[144:145]
	v_mov_b64_e32 v[74:75], v[138:139]
	v_mov_b64_e32 v[76:77], v[140:141]
	v_mov_b64_e32 v[96:97], v[134:135]
	v_mov_b64_e32 v[98:99], v[136:137]
	s_waitcnt vmcnt(1)
	v_pk_mul_f32 v[76:77], v[76:77], v[82:83]
	v_pk_mul_f32 v[82:83], v[84:85], v[94:95] op_sel_hi:[1,0]
	v_cvt_pk_bf16_f32 v84, v58, v59
	v_cvt_pk_bf16_f32 v85, v60, v61
	s_waitcnt vmcnt(0)
	v_pk_mul_f32 v[78:79], v[96:97], v[78:79]
	v_pk_mul_f32 v[70:71], v[70:71], v[82:83]
	v_pk_mul_f32 v[82:83], v[86:87], v[94:95] op_sel_hi:[1,0]
	v_pk_mul_f32 v[80:81], v[98:99], v[80:81]
	v_pk_mul_f32 v[72:73], v[72:73], v[82:83]
	v_pk_mul_f32 v[82:83], v[88:89], v[94:95] op_sel_hi:[1,0]
	v_pk_mul_f32 v[74:75], v[74:75], v[92:93]
	v_pk_mul_f32 v[66:67], v[66:67], v[82:83]
	v_pk_mul_f32 v[82:83], v[90:91], v[94:95] op_sel_hi:[1,0]
	s_nop 0
	v_pk_mul_f32 v[68:69], v[68:69], v[82:83]
	v_cvt_pk_bf16_f32 v82, v62, v63
	v_cvt_pk_bf16_f32 v83, v64, v65
	ds_write_b128 v203, v[82:85]
	v_cvt_pk_bf16_f32 v82, v54, v55
	v_cvt_pk_bf16_f32 v83, v56, v57
	v_cvt_pk_bf16_f32 v84, v50, v51
	v_cvt_pk_bf16_f32 v85, v52, v53
	ds_write_b128 v203, v[82:85] offset:16
	v_cvt_pk_bf16_f32 v82, v78, v79
	v_cvt_pk_bf16_f32 v83, v80, v81
	v_cvt_pk_bf16_f32 v84, v74, v75
	v_cvt_pk_bf16_f32 v85, v76, v77
	ds_write_b128 v203, v[82:85] offset:32
	v_cvt_pk_bf16_f32 v82, v70, v71
	v_cvt_pk_bf16_f32 v83, v72, v73
	v_cvt_pk_bf16_f32 v84, v66, v67
	v_cvt_pk_bf16_f32 v85, v68, v69
	ds_write_b128 v203, v[82:85] offset:48
	s_and_saveexec_b64 s[72:73], s[20:21]
	s_cbranch_execz .LBB0_274
	v_add_u32_e32 v82, s74, v177
	v_ashrrev_i32_e32 v83, 31, v82
	v_readlane_b32 s20, v247, 36
	v_lshlrev_b64 v[82:83], 9, v[82:83]
	v_readlane_b32 s21, v247, 37
	s_lshl_b32 s0, s19, 2
	v_lshlrev_b32_e32 v170, 2, v178
	v_lshl_add_u64 v[82:83], s[20:21], 0, v[82:83]
	v_lshl_add_u64 v[82:83], v[82:83], 0, s[0:1]
	v_lshl_add_u64 v[82:83], v[82:83], 0, v[170:171]
	global_store_dwordx4 v[82:83], v[62:65], off
	global_store_dwordx4 v[82:83], v[58:61], off offset:16
	global_store_dwordx4 v[82:83], v[54:57], off offset:32
	global_store_dwordx4 v[82:83], v[50:53], off offset:48
	global_store_dwordx4 v[82:83], v[78:81], off offset:64
	global_store_dwordx4 v[82:83], v[74:77], off offset:80
	global_store_dwordx4 v[82:83], v[70:73], off offset:96
	global_store_dwordx4 v[82:83], v[66:69], off offset:112

.LBB0_282:
	s_or_b64 exec, exec, s[4:5]
	v_and_b32_e32 v49, 0xffff0000, v14
	v_lshlrev_b32_e32 v48, 16, v14
	v_lshlrev_b32_e32 v39, 16, v6
	v_and_b32_e32 v38, 0xffff0000, v6
	v_lshlrev_b32_e32 v37, 16, v7
	v_and_b32_e32 v36, 0xffff0000, v7
	v_lshlrev_b32_e32 v7, 16, v9
	v_and_b32_e32 v6, 0xffff0000, v9
	v_mul_f32_e32 v9, v49, v49
	v_lshlrev_b32_e32 v54, 16, v15
	v_fmac_f32_e32 v9, v48, v48
	v_and_b32_e32 v55, 0xffff0000, v15
	v_fmac_f32_e32 v9, v54, v54
	v_lshlrev_b32_e32 v56, 16, v16
	v_fmac_f32_e32 v9, v55, v55
	v_and_b32_e32 v57, 0xffff0000, v16
	v_fmac_f32_e32 v9, v56, v56
	v_lshlrev_b32_e32 v58, 16, v17
	v_fmac_f32_e32 v9, v57, v57
	v_and_b32_e32 v59, 0xffff0000, v17
	v_fmac_f32_e32 v9, v58, v58
	v_lshlrev_b32_e32 v47, 16, v10
	v_fmac_f32_e32 v9, v59, v59
	v_and_b32_e32 v46, 0xffff0000, v10
	v_fmac_f32_e32 v9, v47, v47
	v_lshlrev_b32_e32 v45, 16, v11
	v_fmac_f32_e32 v9, v46, v46
	v_and_b32_e32 v44, 0xffff0000, v11
	v_fmac_f32_e32 v9, v45, v45
	v_lshlrev_b32_e32 v43, 16, v12
	v_fmac_f32_e32 v9, v44, v44
	v_and_b32_e32 v42, 0xffff0000, v12
	v_fmac_f32_e32 v9, v43, v43
	v_lshlrev_b32_e32 v41, 16, v13
	v_fmac_f32_e32 v9, v42, v42
	v_and_b32_e32 v40, 0xffff0000, v13
	v_fmac_f32_e32 v9, v41, v41
	v_fmac_f32_e32 v9, v40, v40
	v_fmac_f32_e32 v9, v39, v39
	v_fmac_f32_e32 v9, v38, v38
	v_fmac_f32_e32 v9, v37, v37
	v_lshlrev_b32_e32 v35, 16, v8
	v_fmac_f32_e32 v9, v36, v36
	v_and_b32_e32 v8, 0xffff0000, v8
	v_fmac_f32_e32 v9, v35, v35
	v_fmac_f32_e32 v9, v8, v8
	v_fmac_f32_e32 v9, v7, v7
	v_lshlrev_b32_e32 v17, 16, v2
	v_fmac_f32_e32 v9, v6, v6
	v_and_b32_e32 v16, 0xffff0000, v2
	v_fmac_f32_e32 v9, v17, v17
	v_lshlrev_b32_e32 v15, 16, v3
	v_fmac_f32_e32 v9, v16, v16
	v_and_b32_e32 v14, 0xffff0000, v3
	v_fmac_f32_e32 v9, v15, v15
	v_and_b32_e32 v12, 0xffff0000, v4
	v_lshlrev_b32_e32 v13, 16, v4
	v_fmac_f32_e32 v9, v14, v14
	v_pk_mul_f32 v[2:3], v[12:13], v[12:13]
	v_and_b32_e32 v10, 0xffff0000, v5
	v_add_f32_e32 v3, v3, v9
	v_lshlrev_b32_e32 v11, 16, v5
	v_add_f32_e32 v4, v2, v3
	v_pk_mul_f32 v[2:3], v[10:11], v[10:11]
	s_lshl_b32 s0, s15, 2
	v_add_f32_e32 v3, v3, v4
	v_add_f32_e32 v2, v2, v3
	ds_bpermute_b32 v3, v199, v2
	v_mov_b32_e32 v34, s0
	s_waitcnt lgkmcnt(0)
	s_barrier
	v_add_f32_e32 v2, v2, v3
	v_fmamk_f32 v2, v2, 0x3c800000, v202
	v_rsq_f32_e32 v2, v2
	global_load_dword v170, v34, s[10:11]
	v_mul_f32_e32 v34, 0x3e38aa3b, v2
	v_mov_b64_e32 v[2:3], v[220:221]
	v_mov_b64_e32 v[4:5], v[222:223]
	v_mov_b64_e32 v[50:51], v[216:217]
	v_mov_b64_e32 v[52:53], v[218:219]
	v_mul_f32_e32 v9, v34, v48
	v_mul_f32_e32 v48, v34, v49
	v_mul_f32_e32 v46, v34, v46
	v_mul_f32_e32 v44, v34, v44
	v_mul_f32_e32 v38, v34, v38
	v_mul_f32_e32 v36, v34, v36
	v_mul_f32_e32 v8, v34, v8
	v_mul_f32_e32 v17, v34, v17
	v_mul_f32_e32 v16, v34, v16
	s_waitcnt vmcnt(0)
	v_mul_f32_e32 v9, v50, v9
	v_mul_f32_e32 v48, v51, v48
	v_cvt_pk_bf16_f32 v50, v9, v48
	v_mul_f32_e32 v9, v34, v54
	v_mul_f32_e32 v9, v52, v9
	v_mul_f32_e32 v48, v34, v55
	v_mul_f32_e32 v48, v53, v48
	v_cvt_pk_bf16_f32 v51, v9, v48
	v_mul_f32_e32 v9, v34, v56
	v_mul_f32_e32 v2, v2, v9
	v_mul_f32_e32 v9, v34, v57
	v_mul_f32_e32 v3, v3, v9
	v_cvt_pk_bf16_f32 v52, v2, v3
	v_mul_f32_e32 v2, v34, v58
	v_mul_f32_e32 v3, v34, v59
	v_mul_f32_e32 v2, v4, v2
	v_mul_f32_e32 v3, v5, v3
	v_cvt_pk_bf16_f32 v53, v2, v3
	v_mov_b64_e32 v[2:3], v[228:229]
	v_mov_b64_e32 v[4:5], v[230:231]
	v_mov_b64_e32 v[54:55], v[224:225]
	v_mov_b64_e32 v[56:57], v[226:227]
	v_mul_f32_e32 v9, v34, v47
	s_waitcnt vmcnt(0)
	v_mul_f32_e32 v9, v9, v54
	v_mul_f32_e32 v46, v46, v55
	v_cvt_pk_bf16_f32 v54, v9, v46
	v_mul_f32_e32 v9, v34, v45
	v_mul_f32_e32 v9, v9, v56
	v_mul_f32_e32 v44, v44, v57
	v_cvt_pk_bf16_f32 v55, v9, v44
	v_mul_f32_e32 v9, v34, v43
	v_mul_f32_e32 v2, v9, v2
	v_mul_f32_e32 v9, v34, v42
	v_mul_f32_e32 v3, v9, v3
	v_cvt_pk_bf16_f32 v56, v2, v3
	v_mul_f32_e32 v2, v34, v41
	v_mul_f32_e32 v3, v34, v40
	v_mul_f32_e32 v2, v2, v4
	v_mul_f32_e32 v3, v3, v5
	v_cvt_pk_bf16_f32 v57, v2, v3
	v_mov_b64_e32 v[2:3], v[236:237]
	v_mov_b64_e32 v[4:5], v[238:239]
	v_mov_b64_e32 v[40:41], v[232:233]
	v_mov_b64_e32 v[42:43], v[234:235]
	v_mul_f32_e32 v9, v34, v39
	s_waitcnt vmcnt(1)
	v_mul_f32_e32 v3, v8, v3
	s_waitcnt vmcnt(0)
	v_mul_f32_e32 v9, v9, v40
	v_mul_f32_e32 v38, v38, v41
	v_cvt_pk_bf16_f32 v58, v9, v38
	v_mul_f32_e32 v9, v34, v37
	v_mul_f32_e32 v9, v9, v42
	v_mul_f32_e32 v36, v36, v43
	v_cvt_pk_bf16_f32 v59, v9, v36
	v_mul_f32_e32 v9, v34, v35
	v_mul_f32_e32 v2, v9, v2
	v_cvt_pk_bf16_f32 v60, v2, v3
	v_mul_f32_e32 v2, v34, v7
	v_mul_f32_e32 v3, v34, v6
	v_mul_f32_e32 v2, v2, v4
	v_mul_f32_e32 v3, v3, v5
	v_cvt_pk_bf16_f32 v61, v2, v3
	v_mov_b64_e32 v[2:3], v[248:249]
	v_mov_b64_e32 v[4:5], v[250:251]
	v_mov_b64_e32 v[6:7], v[240:241]
	v_mov_b64_e32 v[8:9], v[242:243]
	s_waitcnt vmcnt(0)
	v_mul_f32_e32 v6, v17, v6
	v_mul_f32_e32 v7, v16, v7
	v_cvt_pk_bf16_f32 v82, v6, v7
	v_mul_f32_e32 v6, v34, v15
	v_mul_f32_e32 v6, v6, v8
	v_mul_f32_e32 v7, v34, v14
	v_mul_f32_e32 v7, v7, v9
	v_cvt_pk_bf16_f32 v83, v6, v7
	v_mul_f32_e32 v6, v34, v13
	v_mul_f32_e32 v2, v6, v2
	v_mul_f32_e32 v6, v34, v12
	v_mul_f32_e32 v3, v6, v3
	v_cvt_pk_bf16_f32 v84, v2, v3
	v_mul_f32_e32 v2, v34, v11
	v_mul_f32_e32 v3, v34, v10
	v_mul_f32_e32 v2, v2, v4
	v_mul_f32_e32 v3, v3, v5
	v_cvt_pk_bf16_f32 v85, v2, v3
	s_setprio 1
	v_or_b32_e32 v2, s17, v1
	v_mad_u32_u24 v189, v2, s6, v195
	ds_read_b128 v[2:5], v189
	v_or_b32_e32 v6, s18, v1
	v_mad_u32_u24 v62, v6, s6, v195
	s_add_i32 s19, s14, 2
	s_add_i32 s18, s14, 3
	s_or_b32 s0, s14, 4
	s_waitcnt lgkmcnt(0)
	v_mfma_f32_32x32x16_bf16 v[146:161], v[2:5], v[50:53], 0
	ds_read_b128 v[2:5], v189 offset:32
	s_waitcnt lgkmcnt(0)
	v_mfma_f32_32x32x16_bf16 v[146:161], v[2:5], v[54:57], v[146:161]
	ds_read_b128 v[2:5], v189 offset:64
	s_waitcnt lgkmcnt(0)
	v_mfma_f32_32x32x16_bf16 v[146:161], v[2:5], v[58:61], v[146:161]
	ds_read_b128 v[2:5], v189 offset:96
	s_waitcnt lgkmcnt(0)
	v_mfma_f32_32x32x16_bf16 v[146:161], v[2:5], v[82:85], v[146:161]
	ds_read_b128 v[2:5], v62
	s_waitcnt lgkmcnt(0)
	v_mfma_f32_32x32x16_bf16 v[66:81], v[2:5], v[50:53], 0
	ds_read_b128 v[2:5], v62 offset:32
	s_waitcnt lgkmcnt(0)
	v_mfma_f32_32x32x16_bf16 v[66:81], v[2:5], v[54:57], v[66:81]
	ds_read_b128 v[2:5], v62 offset:64
	s_waitcnt lgkmcnt(0)
	v_mfma_f32_32x32x16_bf16 v[66:81], v[2:5], v[58:61], v[66:81]
	ds_read_b128 v[2:5], v62 offset:96
	s_waitcnt lgkmcnt(0)
	v_mfma_f32_32x32x16_bf16 v[66:81], v[2:5], v[82:85], v[66:81]
	v_lshl_or_b32 v2, s19, 5, v1
	v_mad_u32_u24 v6, v2, s6, v195
	ds_read_b128 v[2:5], v6
	s_waitcnt lgkmcnt(0)
	v_mfma_f32_32x32x16_bf16 v[34:49], v[2:5], v[50:53], 0
	ds_read_b128 v[2:5], v6 offset:32
	s_waitcnt lgkmcnt(0)
	v_mfma_f32_32x32x16_bf16 v[34:49], v[2:5], v[54:57], v[34:49]
	ds_read_b128 v[2:5], v6 offset:64
	s_waitcnt lgkmcnt(0)
	v_mfma_f32_32x32x16_bf16 v[34:49], v[2:5], v[58:61], v[34:49]
	ds_read_b128 v[2:5], v6 offset:96
	s_waitcnt lgkmcnt(0)
	v_mfma_f32_32x32x16_bf16 v[34:49], v[2:5], v[82:85], v[34:49]
	v_lshl_or_b32 v2, s18, 5, v1
	v_mad_u32_u24 v63, v2, s6, v195
	ds_read_b128 v[2:5], v63
	ds_read_b128 v[86:89], v63 offset:32
	s_waitcnt lgkmcnt(1)
	v_mfma_f32_32x32x16_bf16 v[2:17], v[2:5], v[50:53], 0
	s_waitcnt lgkmcnt(0)
	v_mfma_f32_32x32x16_bf16 v[2:17], v[86:89], v[54:57], v[2:17]
	ds_read_b128 v[86:89], v63 offset:64
	s_waitcnt lgkmcnt(0)
	v_mfma_f32_32x32x16_bf16 v[2:17], v[86:89], v[58:61], v[2:17]
	ds_read_b128 v[86:89], v63 offset:96
	v_lshl_or_b32 v63, s0, 5, v1
	v_mad_u32_u24 v63, v63, s6, v195
	s_waitcnt lgkmcnt(0)
	v_mfma_f32_32x32x16_bf16 v[2:17], v[86:89], v[82:85], v[2:17]
	ds_read_b128 v[86:89], v63
	s_waitcnt lgkmcnt(0)
	v_mfma_f32_32x32x16_bf16 v[98:113], v[86:89], v[50:53], 0
	ds_read_b128 v[50:53], v63 offset:32
	s_waitcnt lgkmcnt(0)
	v_mfma_f32_32x32x16_bf16 v[98:113], v[50:53], v[54:57], v[98:113]
	ds_read_b128 v[50:53], v63 offset:64
	s_waitcnt lgkmcnt(0)
	v_mfma_f32_32x32x16_bf16 v[98:113], v[50:53], v[58:61], v[98:113]
	ds_read_b128 v[50:53], v63 offset:96
	s_waitcnt lgkmcnt(0)
	v_mfma_f32_32x32x16_bf16 v[98:113], v[50:53], v[82:85], v[98:113]
	s_setprio 0
	v_and_b32_e32 v86, 0xffff0000, v30
	v_lshlrev_b32_e32 v65, 16, v30
	v_lshlrev_b32_e32 v55, 16, v22
	v_and_b32_e32 v54, 0xffff0000, v22
	v_lshlrev_b32_e32 v53, 16, v23
	v_and_b32_e32 v52, 0xffff0000, v23
	v_lshlrev_b32_e32 v23, 16, v25
	v_and_b32_e32 v22, 0xffff0000, v25
	v_mul_f32_e32 v25, v86, v86
	v_lshlrev_b32_e32 v87, 16, v31
	v_fmac_f32_e32 v25, v65, v65
	v_and_b32_e32 v88, 0xffff0000, v31
	v_fmac_f32_e32 v25, v87, v87
	v_lshlrev_b32_e32 v89, 16, v32
	v_fmac_f32_e32 v25, v88, v88
	v_and_b32_e32 v90, 0xffff0000, v32
	v_fmac_f32_e32 v25, v89, v89
	v_lshlrev_b32_e32 v91, 16, v33
	v_fmac_f32_e32 v25, v90, v90
	v_and_b32_e32 v92, 0xffff0000, v33
	v_fmac_f32_e32 v25, v91, v91
	v_lshlrev_b32_e32 v64, 16, v26
	v_fmac_f32_e32 v25, v92, v92
	v_and_b32_e32 v63, 0xffff0000, v26
	v_fmac_f32_e32 v25, v64, v64
	v_lshlrev_b32_e32 v61, 16, v27
	v_fmac_f32_e32 v25, v63, v63
	v_and_b32_e32 v60, 0xffff0000, v27
	v_fmac_f32_e32 v25, v61, v61
	v_lshlrev_b32_e32 v59, 16, v28
	v_fmac_f32_e32 v25, v60, v60
	v_and_b32_e32 v58, 0xffff0000, v28
	v_fmac_f32_e32 v25, v59, v59
	v_lshlrev_b32_e32 v57, 16, v29
	v_fmac_f32_e32 v25, v58, v58
	v_and_b32_e32 v56, 0xffff0000, v29
	v_fmac_f32_e32 v25, v57, v57
	v_fmac_f32_e32 v25, v56, v56
	v_fmac_f32_e32 v25, v55, v55
	v_fmac_f32_e32 v25, v54, v54
	v_fmac_f32_e32 v25, v53, v53
	v_lshlrev_b32_e32 v51, 16, v24
	v_fmac_f32_e32 v25, v52, v52
	v_and_b32_e32 v24, 0xffff0000, v24
	v_fmac_f32_e32 v25, v51, v51
	v_fmac_f32_e32 v25, v24, v24
	v_fmac_f32_e32 v25, v23, v23
	v_lshlrev_b32_e32 v33, 16, v18
	v_fmac_f32_e32 v25, v22, v22
	v_and_b32_e32 v32, 0xffff0000, v18
	v_fmac_f32_e32 v25, v33, v33
	v_lshlrev_b32_e32 v31, 16, v19
	v_fmac_f32_e32 v25, v32, v32
	v_and_b32_e32 v30, 0xffff0000, v19
	v_fmac_f32_e32 v25, v31, v31
	v_and_b32_e32 v28, 0xffff0000, v20
	v_lshlrev_b32_e32 v29, 16, v20
	v_fmac_f32_e32 v25, v30, v30
	v_pk_mul_f32 v[18:19], v[28:29], v[28:29]
	v_and_b32_e32 v26, 0xffff0000, v21
	v_add_f32_e32 v19, v19, v25
	v_lshlrev_b32_e32 v27, 16, v21
	v_add_f32_e32 v20, v18, v19
	v_pk_mul_f32 v[18:19], v[26:27], v[26:27]
	s_nop 0
	v_add_f32_e32 v19, v19, v20
	v_add_f32_e32 v18, v18, v19
	ds_bpermute_b32 v19, v199, v18
	s_waitcnt lgkmcnt(0)
	v_add_f32_e32 v18, v18, v19
	v_fmamk_f32 v18, v18, 0x3c800000, v202
	v_rsq_f32_e32 v18, v18
	s_nop 0
	v_mul_f32_e32 v50, 0x3e38aa3b, v18
	v_mov_b64_e32 v[18:19], v[220:221]
	v_mov_b64_e32 v[20:21], v[222:223]
	v_mov_b64_e32 v[82:83], v[216:217]
	v_mov_b64_e32 v[84:85], v[218:219]
	v_mul_f32_e32 v25, v50, v65
	v_mul_f32_e32 v65, v50, v86
	v_mul_f32_e32 v63, v50, v63
	v_mul_f32_e32 v60, v50, v60
	v_mul_f32_e32 v54, v50, v54
	v_mul_f32_e32 v52, v50, v52
	v_mul_f32_e32 v24, v50, v24
	v_mul_f32_e32 v33, v50, v33
	v_mul_f32_e32 v32, v50, v32
	s_waitcnt vmcnt(0)
	v_mul_f32_e32 v25, v82, v25
	v_mul_f32_e32 v65, v83, v65
	v_cvt_pk_bf16_f32 v114, v25, v65
	v_mul_f32_e32 v25, v50, v87
	v_mul_f32_e32 v25, v84, v25
	v_mul_f32_e32 v65, v50, v88
	v_mul_f32_e32 v65, v85, v65
	v_cvt_pk_bf16_f32 v115, v25, v65
	v_mul_f32_e32 v25, v50, v89
	v_mul_f32_e32 v18, v18, v25
	v_mul_f32_e32 v25, v50, v90
	v_mul_f32_e32 v19, v19, v25
	v_cvt_pk_bf16_f32 v116, v18, v19
	v_mul_f32_e32 v18, v50, v91
	v_mul_f32_e32 v19, v50, v92
	v_mul_f32_e32 v18, v20, v18
	v_mul_f32_e32 v19, v21, v19
	v_cvt_pk_bf16_f32 v117, v18, v19
	v_mov_b64_e32 v[18:19], v[228:229]
	v_mov_b64_e32 v[20:21], v[230:231]
	v_mov_b64_e32 v[82:83], v[224:225]
	v_mov_b64_e32 v[84:85], v[226:227]
	v_mul_f32_e32 v25, v50, v64
	s_waitcnt vmcnt(0)
	v_mul_f32_e32 v25, v25, v82
	v_mul_f32_e32 v63, v63, v83
	v_cvt_pk_bf16_f32 v162, v25, v63
	v_mul_f32_e32 v25, v50, v61
	v_mul_f32_e32 v25, v25, v84
	v_mul_f32_e32 v60, v60, v85
	v_cvt_pk_bf16_f32 v163, v25, v60
	v_mul_f32_e32 v25, v50, v59
	v_mul_f32_e32 v18, v25, v18
	v_mul_f32_e32 v25, v50, v58
	v_mul_f32_e32 v19, v25, v19
	v_cvt_pk_bf16_f32 v164, v18, v19
	v_mul_f32_e32 v18, v50, v57
	v_mul_f32_e32 v19, v50, v56
	v_mul_f32_e32 v18, v18, v20
	v_mul_f32_e32 v19, v19, v21
	v_cvt_pk_bf16_f32 v165, v18, v19
	v_mov_b64_e32 v[18:19], v[236:237]
	v_mov_b64_e32 v[20:21], v[238:239]
	v_mov_b64_e32 v[56:57], v[232:233]
	v_mov_b64_e32 v[58:59], v[234:235]
	v_mul_f32_e32 v25, v50, v55
	s_waitcnt vmcnt(1)
	v_mul_f32_e32 v19, v24, v19
	s_waitcnt vmcnt(0)
	v_mul_f32_e32 v25, v25, v56
	v_mul_f32_e32 v54, v54, v57
	v_cvt_pk_bf16_f32 v166, v25, v54
	v_mul_f32_e32 v25, v50, v53
	v_mul_f32_e32 v25, v25, v58
	v_mul_f32_e32 v52, v52, v59
	v_cvt_pk_bf16_f32 v167, v25, v52
	v_mul_f32_e32 v25, v50, v51
	v_mul_f32_e32 v18, v25, v18
	v_cvt_pk_bf16_f32 v168, v18, v19
	v_mul_f32_e32 v18, v50, v23
	v_mul_f32_e32 v19, v50, v22
	v_mul_f32_e32 v18, v18, v20
	v_mul_f32_e32 v19, v19, v21
	v_cvt_pk_bf16_f32 v169, v18, v19
	v_mov_b64_e32 v[18:19], v[248:249]
	v_mov_b64_e32 v[20:21], v[250:251]
	v_mov_b64_e32 v[22:23], v[240:241]
	v_mov_b64_e32 v[24:25], v[242:243]
	s_waitcnt vmcnt(0)
	v_mul_f32_e32 v22, v33, v22
	v_mul_f32_e32 v23, v32, v23
	v_cvt_pk_bf16_f32 v208, v22, v23
	v_mul_f32_e32 v22, v50, v31
	v_mul_f32_e32 v22, v22, v24
	v_mul_f32_e32 v23, v50, v30
	v_mul_f32_e32 v23, v23, v25
	v_cvt_pk_bf16_f32 v209, v22, v23
	v_mul_f32_e32 v22, v50, v29
	v_mul_f32_e32 v18, v22, v18
	v_mul_f32_e32 v22, v50, v28
	v_mul_f32_e32 v19, v22, v19
	v_cvt_pk_bf16_f32 v210, v18, v19
	v_mul_f32_e32 v18, v50, v27
	v_mul_f32_e32 v19, v50, v26
	v_mul_f32_e32 v18, v18, v20
	v_mul_f32_e32 v19, v19, v21
	v_cvt_pk_bf16_f32 v211, v18, v19
	s_setprio 1
	ds_read_b128 v[18:21], v62
	ds_read_b128 v[22:25], v62 offset:32
	s_waitcnt lgkmcnt(1)
	v_mfma_f32_32x32x16_bf16 v[130:145], v[18:21], v[114:117], 0
	ds_read_b128 v[18:21], v62 offset:64
	s_waitcnt lgkmcnt(1)
	v_mfma_f32_32x32x16_bf16 v[130:145], v[22:25], v[162:165], v[130:145]
	s_waitcnt lgkmcnt(0)
	v_mfma_f32_32x32x16_bf16 v[130:145], v[18:21], v[166:169], v[130:145]
	ds_read_b128 v[18:21], v62 offset:96
	s_waitcnt lgkmcnt(0)
	v_mfma_f32_32x32x16_bf16 v[130:145], v[18:21], v[208:211], v[130:145]
	v_add_u32_e32 v18, s17, v196
	v_mad_u32_u24 v26, v18, s6, v195
	ds_read_b128 v[18:21], v26
	ds_read_b128 v[22:25], v26 offset:32
	s_waitcnt lgkmcnt(1)
	v_mfma_f32_32x32x16_bf16 v[82:97], v[18:21], v[114:117], 0
	ds_read_b128 v[18:21], v26 offset:64
	s_waitcnt lgkmcnt(1)
	v_mfma_f32_32x32x16_bf16 v[82:97], v[22:25], v[162:165], v[82:97]
	s_waitcnt lgkmcnt(0)
	v_mfma_f32_32x32x16_bf16 v[82:97], v[18:21], v[166:169], v[82:97]
	ds_read_b128 v[18:21], v26 offset:96
	s_waitcnt lgkmcnt(0)
	v_mfma_f32_32x32x16_bf16 v[82:97], v[18:21], v[208:211], v[82:97]
	v_add_u32_e32 v18, s17, v197
	v_mad_u32_u24 v26, v18, s6, v195
	ds_read_b128 v[18:21], v26
	ds_read_b128 v[22:25], v26 offset:32
	s_waitcnt lgkmcnt(1)
	v_mfma_f32_32x32x16_bf16 v[50:65], v[18:21], v[114:117], 0
	ds_read_b128 v[18:21], v26 offset:64
	s_waitcnt lgkmcnt(1)
	v_mfma_f32_32x32x16_bf16 v[50:65], v[22:25], v[162:165], v[50:65]
	s_waitcnt lgkmcnt(0)
	v_mfma_f32_32x32x16_bf16 v[50:65], v[18:21], v[166:169], v[50:65]
	ds_read_b128 v[18:21], v26 offset:96
	s_waitcnt lgkmcnt(0)
	v_mfma_f32_32x32x16_bf16 v[50:65], v[18:21], v[208:211], v[50:65]
	ds_read_b128 v[18:21], v189 offset:18432
	ds_read_b128 v[118:121], v189 offset:18464
	ds_read_b128 v[212:215], v189 offset:23072
	s_waitcnt lgkmcnt(2)
	v_mfma_f32_32x32x16_bf16 v[18:33], v[18:21], v[114:117], 0
	s_waitcnt lgkmcnt(1)
	v_mfma_f32_32x32x16_bf16 v[18:33], v[118:121], v[162:165], v[18:33]
	ds_read_b128 v[118:121], v189 offset:18496
	s_waitcnt lgkmcnt(0)
	v_mfma_f32_32x32x16_bf16 v[18:33], v[118:121], v[166:169], v[18:33]
	ds_read_b128 v[118:121], v189 offset:18528
	s_waitcnt lgkmcnt(0)
	v_mfma_f32_32x32x16_bf16 v[18:33], v[118:121], v[208:211], v[18:33]
	ds_read_b128 v[118:121], v189 offset:23040
	s_waitcnt lgkmcnt(0)
	v_mfma_f32_32x32x16_bf16 v[114:129], v[118:121], v[114:117], 0
	v_mfma_f32_32x32x16_bf16 v[114:129], v[212:215], v[162:165], v[114:129]
	ds_read_b128 v[162:165], v189 offset:23104
	s_waitcnt lgkmcnt(0)
	v_mfma_f32_32x32x16_bf16 v[114:129], v[162:165], v[166:169], v[114:129]
	ds_read_b128 v[162:165], v189 offset:23136
	s_waitcnt lgkmcnt(0)
	v_mfma_f32_32x32x16_bf16 v[114:129], v[162:165], v[208:211], v[114:129]
	s_setprio 0
	s_cmp_lg_u32 s16, 0
	v_mov_b32_e32 v162, 0xf149f2ca
	s_cselect_b64 s[4:5], -1, 0
	s_cmp_eq_u32 s16, 0
	v_mov_b32_e32 v215, 0xf149f2ca
	v_mov_b32_e32 v210, 0xf149f2ca
	v_mov_b32_e32 v211, 0xf149f2ca
	v_mov_b32_e32 v213, 0xf149f2ca
	v_mov_b32_e32 v214, 0xf149f2ca
	v_mov_b32_e32 v208, 0xf149f2ca
	v_mov_b32_e32 v209, 0xf149f2ca
	v_mov_b32_e32 v212, 0xf149f2ca
	v_mov_b32_e32 v191, 0xf149f2ca
	v_mov_b32_e32 v189, 0xf149f2ca
	v_mov_b32_e32 v169, 0xf149f2ca
	v_mov_b32_e32 v168, 0xf149f2ca
	v_mov_b32_e32 v167, 0xf149f2ca
	v_mov_b32_e32 v166, 0xf149f2ca
	v_mov_b32_e32 v165, 0xf149f2ca
	v_mov_b32_e32 v164, 0xf149f2ca
	v_mov_b32_e32 v163, 0xf149f2ca
	s_cbranch_scc1 .LBB0_284
	v_readlane_b32 s20, v247, 40
	v_readlane_b32 s21, v247, 41
	v_cndmask_b32_e64 v191, v153, v207, s[90:91]
	v_cndmask_b32_e64 v189, v154, v207, s[88:89]
	v_cndmask_b32_e64 v210, v146, v207, s[20:21]
	v_readlane_b32 s20, v247, 42
	v_readlane_b32 s21, v247, 43
	v_cndmask_b32_e64 v169, v155, v207, s[24:25]
	v_cndmask_b32_e64 v168, v156, v207, s[26:27]
	v_cndmask_b32_e64 v211, v147, v207, s[20:21]
	v_readlane_b32 s20, v247, 44
	v_readlane_b32 s21, v247, 45
	v_max3_f32 v146, v210, s23, v211
	v_cndmask_b32_e64 v167, v157, v207, s[28:29]
	v_cndmask_b32_e64 v213, v148, v207, s[20:21]
	v_readlane_b32 s20, v247, 46
	v_readlane_b32 s21, v247, 47
	v_cndmask_b32_e64 v166, v158, v207, s[30:31]
	v_cndmask_b32_e64 v165, v159, v207, s[34:35]
	v_cndmask_b32_e64 v214, v149, v207, s[20:21]
	v_readlane_b32 s20, v247, 48
	v_readlane_b32 s21, v247, 49
	v_max3_f32 v146, v146, v213, v214
	v_cndmask_b32_e64 v164, v160, v207, s[36:37]
	v_cndmask_b32_e64 v208, v150, v207, s[20:21]
	v_readlane_b32 s20, v247, 50
	v_readlane_b32 s21, v247, 51
	v_cndmask_b32_e64 v163, v161, v207, s[38:39]
	s_nop 0
	v_cndmask_b32_e64 v209, v151, v207, s[20:21]
	v_readlane_b32 s20, v247, 52
	v_readlane_b32 s21, v247, 53
	v_max3_f32 v146, v146, v208, v209
	s_nop 0
	v_cndmask_b32_e64 v212, v152, v207, s[20:21]
	v_max3_f32 v146, v146, v212, v191
	v_max3_f32 v146, v146, v189, v169
	v_max3_f32 v146, v146, v168, v167
	v_max3_f32 v146, v146, v166, v165
	v_max3_f32 v215, v146, v164, v163

	.amdhsa_kernel _Z14fwd_megakernel4Args
		.amdhsa_group_segment_fixed_size 0
		.amdhsa_private_segment_fixed_size 0
		.amdhsa_kernarg_size 432
		.amdhsa_user_sgpr_count 2
		.amdhsa_user_sgpr_dispatch_ptr 0
		.amdhsa_user_sgpr_queue_ptr 0
		.amdhsa_user_sgpr_kernarg_segment_ptr 1
		.amdhsa_user_sgpr_dispatch_id 0
		.amdhsa_user_sgpr_kernarg_preload_length 0
		.amdhsa_user_sgpr_kernarg_preload_offset 0
		.amdhsa_user_sgpr_private_segment_size 0
		.amdhsa_uses_dynamic_stack 0
		.amdhsa_enable_private_segment 0
		.amdhsa_system_sgpr_workgroup_id_x 1
		.amdhsa_system_sgpr_workgroup_id_y 0
		.amdhsa_system_sgpr_workgroup_id_z 0
		.amdhsa_system_sgpr_workgroup_info 0
		.amdhsa_system_vgpr_workitem_id 0
		.amdhsa_next_free_vgpr 256
		.amdhsa_next_free_sgpr 98
		.amdhsa_accum_offset 256
		.amdhsa_reserve_vcc 1
		.amdhsa_float_round_mode_32 0
		.amdhsa_float_round_mode_16_64 0
		.amdhsa_float_denorm_mode_32 3
		.amdhsa_float_denorm_mode_16_64 3
		.amdhsa_dx10_clamp 1
		.amdhsa_ieee_mode 1
		.amdhsa_fp16_overflow 0
		.amdhsa_tg_split 0
		.amdhsa_exception_fp_ieee_invalid_op 0
		.amdhsa_exception_fp_denorm_src 0
		.amdhsa_exception_fp_ieee_div_zero 0
		.amdhsa_exception_fp_ieee_overflow 0
		.amdhsa_exception_fp_ieee_underflow 0
		.amdhsa_exception_fp_ieee_inexact 0
		.amdhsa_exception_int_div_zero 0
	.end_amdhsa_kernel

amdhsa.kernels:
  - .agpr_count:     0
    .args:
      - .offset:         0
        .size:           176
        .value_kind:     by_value
      - .offset:         176
        .size:           4
        .value_kind:     hidden_block_count_x
      - .offset:         180
        .size:           4
        .value_kind:     hidden_block_count_y
      - .offset:         184
        .size:           4
        .value_kind:     hidden_block_count_z
      - .offset:         188
        .size:           2
        .value_kind:     hidden_group_size_x
      - .offset:         190
        .size:           2
        .value_kind:     hidden_group_size_y
      - .offset:         192
        .size:           2
        .value_kind:     hidden_group_size_z
      - .offset:         194
        .size:           2
        .value_kind:     hidden_remainder_x
      - .offset:         196
        .size:           2
        .value_kind:     hidden_remainder_y
      - .offset:         198
        .size:           2
        .value_kind:     hidden_remainder_z
      - .offset:         216
        .size:           8
        .value_kind:     hidden_global_offset_x
      - .offset:         224
        .size:           8
        .value_kind:     hidden_global_offset_y
      - .offset:         232
        .size:           8
        .value_kind:     hidden_global_offset_z
      - .offset:         240
        .size:           2
        .value_kind:     hidden_grid_dims
      - .offset:         296
        .size:           4
        .value_kind:     hidden_dynamic_lds_size
    .group_segment_fixed_size: 0
    .kernarg_segment_align: 8
    .kernarg_segment_size: 432
    .language:       OpenCL C
    .language_version:
      - 2
      - 0
    .max_flat_workgroup_size: 512
    .name:           _Z14fwd_megakernel4Args
    .private_segment_fixed_size: 0
    .sgpr_count:     104
    .sgpr_spill_count: 56
    .symbol:         _Z14fwd_megakernel4Args.kd
    .uniform_work_group_size: 1
    .uses_dynamic_stack: false
    .vgpr_count:     256
    .vgpr_spill_count: 0
    .wavefront_size: 64
